# init_rows: 64-lane sum reduction via DPP + permlane swaps instead of six ds_bpermute round trips (bit-identical)
# speedup vs baseline: 1.0032x; 1.0001x over previous
; __device__ __forceinline__ float lane_xor(float v, int lane, int o) { return __builtin_bit_cast(float, __builtin_amdgcn_ds_bpermute((lane ^ o) << 2, __builtin_bit_cast(int, v))); }
; __device__ __forceinline__ float wave_sum(float v, int lane) {
; #pragma unroll
;     for (int o = 1; o < 64; o <<= 1) v += lane_xor(v, lane, o);
;     return v;
; __device__ __forceinline__ void init_rows(const float* xp, const float* xs, const float* meta, float* LEAD, float* OUT, const float* gain, bf16_t* XN, float* SS, int gw, int ngw) {
;     ...
;         float sq = 0.f;
; #pragma unroll
;         for (int j = 0; j < 4; ++j) sq += (v[j].x * v[j].x + v[j].y * v[j].y) + (v[j].z * v[j].z + v[j].w * v[j].w);
;         sq = wave_sum(sq, lane);
;         if (lane == 0) SS[r] = sq;
.LBB0_82:
	s_waitcnt vmcnt(1)
	v_mul_f32_e32 v47, v31, v31
	v_mul_f32_e32 v48, v33, v33
	v_fmac_f32_e32 v47, v30, v30
	v_fmac_f32_e32 v48, v32, v32
	v_add_f32_e32 v47, v47, v48
	s_waitcnt vmcnt(0)
	v_mul_f32_e32 v48, v27, v27
	v_mul_f32_e32 v49, v29, v29
	v_fmac_f32_e32 v48, v26, v26
	v_fmac_f32_e32 v49, v28, v28
	v_add_f32_e32 v48, v48, v49
	v_add_f32_e32 v47, v47, v48
	v_mul_f32_e32 v48, v19, v19
	v_mul_f32_e32 v49, v21, v21
	v_mul_f32_e32 v35, v35, v35
	v_fmac_f32_e32 v48, v18, v18
	v_fmac_f32_e32 v49, v20, v20
	v_fmac_f32_e32 v35, v34, v34
	v_mul_f32_e32 v34, v37, v37
	v_add_f32_e32 v48, v48, v49
	v_fmac_f32_e32 v34, v36, v36
	v_add_f32_e32 v47, v48, v47
	v_add_f32_e32 v34, v35, v34
	v_add_f32_e32 v34, v34, v47
	s_nop 1
	v_add_f32_dpp v34, v34, v34 quad_perm:[1,0,3,2] row_mask:0xf bank_mask:0xf
	s_nop 1
	v_add_f32_dpp v34, v34, v34 quad_perm:[2,3,0,1] row_mask:0xf bank_mask:0xf
	s_nop 1
	v_add_f32_dpp v34, v34, v34 row_half_mirror row_mask:0xf bank_mask:0xf
	s_nop 1
	v_add_f32_dpp v34, v34, v34 row_mirror row_mask:0xf bank_mask:0xf
	v_mov_b32_e32 v35, v34
	s_nop 1
	v_permlane16_swap_b32_e32 v34, v35
	v_add_f32_e32 v34, v34, v35
	v_mov_b32_e32 v35, v34
	s_nop 1
	v_permlane32_swap_b32_e32 v34, v35
	v_add_f32_e32 v34, v34, v35
	s_and_saveexec_b64 s[24:25], s[4:5]
	s_cbranch_execz .LBB0_84
	s_load_dwordx2 s[26:27], s[0:1], 0xb0
	s_waitcnt lgkmcnt(0)
	s_add_u32 s26, s26, s36
	s_addc_u32 s27, s27, s37
	global_store_dword v39, v34, s[26:27]
